# v044 + grid barrier: non-leader blocks poll the top generation word directly, XCD republish removed
# speedup vs baseline: 1.0056x; 1.0056x over previous
.LBB0_69:
	s_lshl_b32 s8, s3, 8
	s_add_u32 s8, s34, s8
	s_addc_u32 s9, s35, 0
	v_mov_b32_e32 v3, 0x1000
	v_mov_b32_e32 v5, 1
	global_atomic_add v5, v3, v5, s[8:9] offset:1024 sc0
	v_cvt_f32_u32_e32 v3, v4
	v_sub_u32_e32 v6, 0, v4
	v_rcp_iflag_f32_e32 v3, v3
	s_nop 0
	v_mul_f32_e32 v3, 0x4f7ffffe, v3
	v_cvt_u32_f32_e32 v3, v3
	v_mul_lo_u32 v6, v6, v3
	v_mul_hi_u32 v6, v3, v6
	v_add_u32_e32 v3, v3, v6
	s_waitcnt vmcnt(0)
	v_mul_hi_u32 v3, v5, v3
	v_mul_lo_u32 v6, v3, v4
	v_sub_u32_e32 v6, v5, v6
	v_add_u32_e32 v7, 1, v3
	v_cmp_ge_u32_e32 vcc, v6, v4
	v_add_u32_e32 v5, 1, v5
	s_nop 0
	v_cndmask_b32_e32 v3, v3, v7, vcc
	v_sub_u32_e32 v7, v6, v4
	v_cndmask_b32_e32 v6, v6, v7, vcc
	v_add_u32_e32 v7, 1, v3
	v_cmp_ge_u32_e32 vcc, v6, v4
	s_nop 1
	v_cndmask_b32_e32 v3, v3, v7, vcc
	v_mul_lo_u32 v6, v4, v3
	v_add_u32_e32 v4, v6, v4
	v_cmp_ne_u32_e32 vcc, v5, v4
	s_and_saveexec_b64 s[14:15], vcc
	s_xor_b64 s[14:15], exec, s[14:15]
	s_cbranch_execz .LBB0_83
	s_waitcnt lgkmcnt(0)
	s_add_u32 s20, s38, 0x1d6c5500
	s_addc_u32 s21, s39, 0
	v_mov_b32_e32 v2, 0
	global_load_dword v2, v2, s[20:21] sc1
	s_waitcnt vmcnt(0)
	v_cmp_eq_u32_e32 vcc, v2, v3
	s_and_saveexec_b64 s[16:17], vcc
	s_cbranch_execz .LBB0_82
	s_add_u32 s18, s38, 0x1d6c2200
	s_addc_u32 s19, s39, 0
	s_mov_b32 s48, 1
	s_mov_b64 s[22:23], 0
	v_mov_b32_e32 v2, 0
	s_branch .LBB0_73

.LBB0_100:
	s_or_b64 exec, exec, s[14:15]
	v_mov_b32_e32 v2, 0x2000
	v_mov_b32_e32 v3, 1
	s_waitcnt vmcnt(0)
	buffer_inv sc1
	s_waitcnt vmcnt(0)

.LBB0_451:
	s_lshl_b32 s8, s3, 8
	s_add_u32 s8, s34, s8
	s_addc_u32 s9, s35, 0
	v_mov_b32_e32 v3, 0x1000
	v_mov_b32_e32 v5, 1
	global_atomic_add v5, v3, v5, s[8:9] offset:1024 sc0
	v_cvt_f32_u32_e32 v3, v4
	v_sub_u32_e32 v6, 0, v4
	v_rcp_iflag_f32_e32 v3, v3
	s_nop 0
	v_mul_f32_e32 v3, 0x4f7ffffe, v3
	v_cvt_u32_f32_e32 v3, v3
	v_mul_lo_u32 v6, v6, v3
	v_mul_hi_u32 v6, v3, v6
	v_add_u32_e32 v3, v3, v6
	s_waitcnt vmcnt(0)
	v_mul_hi_u32 v3, v5, v3
	v_mul_lo_u32 v6, v3, v4
	v_sub_u32_e32 v6, v5, v6
	v_add_u32_e32 v7, 1, v3
	v_cmp_ge_u32_e32 vcc, v6, v4
	v_add_u32_e32 v5, 1, v5
	s_nop 0
	v_cndmask_b32_e32 v3, v3, v7, vcc
	v_sub_u32_e32 v7, v6, v4
	v_cndmask_b32_e32 v6, v6, v7, vcc
	v_add_u32_e32 v7, 1, v3
	v_cmp_ge_u32_e32 vcc, v6, v4
	s_nop 1
	v_cndmask_b32_e32 v3, v3, v7, vcc
	v_mul_lo_u32 v6, v4, v3
	v_add_u32_e32 v4, v6, v4
	v_cmp_ne_u32_e32 vcc, v5, v4
	s_and_saveexec_b64 s[10:11], vcc
	s_xor_b64 s[10:11], exec, s[10:11]
	s_cbranch_execz .LBB0_465
	s_waitcnt lgkmcnt(0)
	s_add_u32 s16, s38, 0x1d6c5500
	s_addc_u32 s17, s39, 0
	v_mov_b32_e32 v2, 0
	global_load_dword v2, v2, s[16:17] sc1
	s_waitcnt vmcnt(0)
	v_cmp_eq_u32_e32 vcc, v2, v3
	s_and_saveexec_b64 s[12:13], vcc
	s_cbranch_execz .LBB0_464
	s_add_u32 s14, s38, 0x1d6c2200
	s_addc_u32 s15, s39, 0
	s_mov_b32 s44, 1
	s_mov_b64 s[18:19], 0
	v_mov_b32_e32 v2, 0
	s_branch .LBB0_455

.LBB0_482:
	s_or_b64 exec, exec, s[10:11]
	v_mov_b32_e32 v2, 0x2000
	v_mov_b32_e32 v3, 1
	s_waitcnt vmcnt(0)
	buffer_inv sc1
	s_waitcnt vmcnt(0)

.LBB0_1711:
	s_lshl_b32 s6, s3, 8
	s_add_u32 s6, s34, s6
	s_addc_u32 s7, s35, 0
	v_mov_b32_e32 v3, 0x1000
	v_mov_b32_e32 v5, 1
	global_atomic_add v5, v3, v5, s[6:7] offset:1024 sc0
	v_cvt_f32_u32_e32 v3, v4
	v_sub_u32_e32 v6, 0, v4
	v_rcp_iflag_f32_e32 v3, v3
	s_nop 0
	v_mul_f32_e32 v3, 0x4f7ffffe, v3
	v_cvt_u32_f32_e32 v3, v3
	v_mul_lo_u32 v6, v6, v3
	v_mul_hi_u32 v6, v3, v6
	v_add_u32_e32 v3, v3, v6
	s_waitcnt vmcnt(0)
	v_mul_hi_u32 v3, v5, v3
	v_mul_lo_u32 v6, v3, v4
	v_sub_u32_e32 v6, v5, v6
	v_add_u32_e32 v7, 1, v3
	v_cmp_ge_u32_e32 vcc, v6, v4
	v_add_u32_e32 v5, 1, v5
	s_nop 0
	v_cndmask_b32_e32 v3, v3, v7, vcc
	v_sub_u32_e32 v7, v6, v4
	v_cndmask_b32_e32 v6, v6, v7, vcc
	v_add_u32_e32 v7, 1, v3
	v_cmp_ge_u32_e32 vcc, v6, v4
	s_nop 1
	v_cndmask_b32_e32 v3, v3, v7, vcc
	v_mul_lo_u32 v6, v4, v3
	v_add_u32_e32 v4, v6, v4
	v_cmp_ne_u32_e32 vcc, v5, v4
	s_and_saveexec_b64 s[8:9], vcc
	s_xor_b64 s[8:9], exec, s[8:9]
	s_cbranch_execz .LBB0_1725
	s_waitcnt lgkmcnt(0)
	s_add_u32 s14, s38, 0x1d6c5500
	s_addc_u32 s15, s39, 0
	v_mov_b32_e32 v2, 0
	global_load_dword v2, v2, s[14:15] sc1
	s_waitcnt vmcnt(0)
	v_cmp_eq_u32_e32 vcc, v2, v3
	s_and_saveexec_b64 s[10:11], vcc
	s_cbranch_execz .LBB0_1724
	s_add_u32 s12, s38, 0x1d6c2200
	s_addc_u32 s13, s39, 0
	s_mov_b32 s28, 1
	s_mov_b64 s[16:17], 0
	v_mov_b32_e32 v2, 0
	s_branch .LBB0_1715

.LBB0_1742:
	s_or_b64 exec, exec, s[8:9]
	v_mov_b32_e32 v2, 0x2000
	v_mov_b32_e32 v3, 1
	s_waitcnt vmcnt(0)
	buffer_inv sc1
	s_waitcnt vmcnt(0)

.LBB0_2154:
	s_lshl_b32 s3, s3, 8
	s_add_u32 s6, s34, s3
	s_addc_u32 s7, s35, 0
	v_mov_b32_e32 v3, 0x1000
	v_mov_b32_e32 v5, 1
	global_atomic_add v5, v3, v5, s[6:7] offset:1024 sc0
	v_cvt_f32_u32_e32 v3, v4
	v_sub_u32_e32 v6, 0, v4
	v_rcp_iflag_f32_e32 v3, v3
	s_nop 0
	v_mul_f32_e32 v3, 0x4f7ffffe, v3
	v_cvt_u32_f32_e32 v3, v3
	v_mul_lo_u32 v6, v6, v3
	v_mul_hi_u32 v6, v3, v6
	v_add_u32_e32 v3, v3, v6
	s_waitcnt vmcnt(0)
	v_mul_hi_u32 v3, v5, v3
	v_mul_lo_u32 v6, v3, v4
	v_sub_u32_e32 v6, v5, v6
	v_add_u32_e32 v7, 1, v3
	v_cmp_ge_u32_e32 vcc, v6, v4
	v_add_u32_e32 v5, 1, v5
	s_nop 0
	v_cndmask_b32_e32 v3, v3, v7, vcc
	v_sub_u32_e32 v7, v6, v4
	v_cndmask_b32_e32 v6, v6, v7, vcc
	v_add_u32_e32 v7, 1, v3
	v_cmp_ge_u32_e32 vcc, v6, v4
	s_nop 1
	v_cndmask_b32_e32 v3, v3, v7, vcc
	v_mul_lo_u32 v6, v4, v3
	v_add_u32_e32 v4, v6, v4
	v_cmp_ne_u32_e32 vcc, v5, v4
	s_and_saveexec_b64 s[8:9], vcc
	s_xor_b64 s[8:9], exec, s[8:9]
	s_cbranch_execz .LBB0_2168
	s_waitcnt lgkmcnt(0)
	s_add_u32 s14, s38, 0x1d6c5500
	s_addc_u32 s15, s39, 0
	v_mov_b32_e32 v2, 0
	global_load_dword v2, v2, s[14:15] sc1
	s_waitcnt vmcnt(0)
	v_cmp_eq_u32_e32 vcc, v2, v3
	s_and_saveexec_b64 s[10:11], vcc
	s_cbranch_execz .LBB0_2167
	s_add_u32 s12, s38, 0x1d6c2200
	s_addc_u32 s13, s39, 0
	s_mov_b32 s3, 1
	s_mov_b64 s[16:17], 0
	v_mov_b32_e32 v2, 0
	s_branch .LBB0_2158
